# plus phase-3 first-half mask-word wait sunk below the (now up-front) QK^T reads and MFMAs
# baseline (speedup 1.0000x reference)
; #define MFMA16(a, b, c) __builtin_amdgcn_mfma_f32_16x16x32_f16((a), (b), (c), 0, 0, 0)
; DI void qk_tile2(f32x4 (&sa)[4], f32x4 (&sb)[4], const char* sK, const bf16x8 (&qa)[2], const bf16x8 (&qb)[2], int lr, int g) {
; #pragma unroll
;   for (int kt = 0; kt < 4; ++kt) {
;     const bf16x8 k0 = *(const bf16x8*)(sK + (kt * 16 + lr) * 128 + ((g ^ ((lr >> 1) & 7)) << 4)), k1 = *(const bf16x8*)(sK + (kt * 16 + lr) * 128 + (((4 + g) ^ ((lr >> 1) & 7)) << 4));
;     sa[kt] = MFMA16(k0, qa[0], ((f32x4){0.f, 0.f, 0.f, 0.f})); sb[kt] = MFMA16(k0, qb[0], ((f32x4){0.f, 0.f, 0.f, 0.f}));
;     sa[kt] = MFMA16(k1, qa[1], sa[kt]); sb[kt] = MFMA16(k1, qb[1], sb[kt]);
;   }
; }
.LBB0_1079:
	v_readlane_b32 s16, v254, 55
	s_add_i32 s1, s15, -2
	v_readlane_b32 s18, v254, 57
	v_readlane_b32 s19, v254, 58
	v_cmp_le_i32_e32 vcc, s1, v107
	v_readlane_b32 s17, v254, 56
	v_lshl_add_u64 v[122:123], s[18:19], 0, v[112:113]
	s_and_saveexec_b64 s[12:13], vcc
	s_cbranch_execz .LBB0_1081
	v_add_co_u32_e32 v80, vcc, 0x1b900000, v122
	s_mov_b32 s16, 0xff800000
	s_nop 0
	v_addc_co_u32_e32 v81, vcc, 0, v123, vcc
	global_load_dwordx2 v[126:127], v[80:81], off
	v_add_co_u32_e32 v80, vcc, 0x1b902000, v122
	s_nop 1
	v_addc_co_u32_e32 v81, vcc, 0, v123, vcc
	global_load_dwordx2 v[128:129], v[80:81], off
	ds_read_b128 v[200:203], v139
	ds_read_b128 v[204:207], v140
	ds_read_b128 v[208:211], v139 offset:2048
	ds_read_b128 v[212:215], v140 offset:2048
	ds_read_b128 v[220:223], v139 offset:4096
	ds_read_b128 v[224:227], v140 offset:4096
	ds_read_b128 v[228:231], v139 offset:6144
	ds_read_b128 v[232:235], v140 offset:6144
	s_waitcnt lgkmcnt(7)
	v_mfma_f32_16x16x32_f16 v[88:91], v[200:203], v[0:3], 0
	v_mfma_f32_16x16x32_f16 v[80:83], v[200:203], v[4:7], 0
	s_waitcnt lgkmcnt(6)
	v_mfma_f32_16x16x32_f16 v[142:145], v[204:207], v[8:11], v[88:91]
	v_mfma_f32_16x16x32_f16 v[154:157], v[204:207], v[12:15], v[80:83]
	s_nop 3
	s_waitcnt lgkmcnt(5)
	v_mfma_f32_16x16x32_f16 v[88:91], v[208:211], v[0:3], 0
	v_mfma_f32_16x16x32_f16 v[80:83], v[208:211], v[4:7], 0
	s_waitcnt lgkmcnt(4)
	v_mfma_f32_16x16x32_f16 v[100:103], v[212:215], v[8:11], v[88:91]
	v_mfma_f32_16x16x32_f16 v[96:99], v[212:215], v[12:15], v[80:83]
	s_nop 4
	s_waitcnt lgkmcnt(3)
	v_mfma_f32_16x16x32_f16 v[84:87], v[220:223], v[0:3], 0
	v_mfma_f32_16x16x32_f16 v[80:83], v[220:223], v[4:7], 0
	s_waitcnt lgkmcnt(2)
	v_mfma_f32_16x16x32_f16 v[84:87], v[224:227], v[8:11], v[84:87]
	v_mfma_f32_16x16x32_f16 v[80:83], v[224:227], v[12:15], v[80:83]
	s_waitcnt lgkmcnt(1)
	v_mfma_f32_16x16x32_f16 v[158:161], v[228:231], v[0:3], 0
	v_mfma_f32_16x16x32_f16 v[162:165], v[228:231], v[4:7], 0
	s_waitcnt lgkmcnt(0)
	v_mfma_f32_16x16x32_f16 v[88:91], v[232:235], v[8:11], v[158:161]
	s_waitcnt vmcnt(0)
	v_lshrrev_b32_e32 v147, v132, v126
	v_and_b32_e32 v130, 1, v147
	v_cmp_eq_u32_e32 vcc, 1, v130
	v_bfe_i32 v141, v147, 1, 1
	v_lshrrev_b32_e32 v126, v138, v126
	s_nop 4
	v_cndmask_b32_e32 v159, v187, v142, vcc
	v_bfe_i32 v142, v147, 2, 1
	v_mfma_f32_16x16x32_f16 v[92:95], v[232:235], v[12:15], v[162:165]
	s_waitcnt vmcnt(0)
	v_lshrrev_b32_e32 v158, v132, v128
	v_and_b32_e32 v130, 1, v158
	v_cmp_eq_u32_e32 vcc, 1, v130
	v_lshrrev_b32_e32 v128, v138, v128
	s_nop 0
	v_cndmask_b32_e32 v130, v187, v154, vcc
	v_bfi_b32 v154, v141, v143, v187
	v_and_b32_e32 v141, 2, v158
	v_cmp_ne_u32_e32 vcc, 0, v141
	v_bfe_i32 v143, v147, 3, 1
	v_bfe_i32 v147, v126, 0, 1
	v_cndmask_b32_e32 v141, v187, v155, vcc
	v_bfi_b32 v144, v142, v144, v187
	v_and_b32_e32 v142, 4, v158
	v_cmp_ne_u32_e32 vcc, 0, v142
	s_nop 1
	v_cndmask_b32_e32 v142, v187, v156, vcc
	v_bfi_b32 v145, v143, v145, v187
	v_and_b32_e32 v143, 8, v158
	v_cmp_ne_u32_e32 vcc, 0, v143
	s_nop 1
	v_cndmask_b32_e32 v143, v187, v157, vcc
	v_bfi_b32 v100, v147, v100, v187
	v_and_b32_e32 v147, 1, v128
	v_cmp_eq_u32_e32 vcc, 1, v147
	s_nop 1
	v_cndmask_b32_e32 v147, v187, v96, vcc
	v_and_b32_e32 v96, 2, v126
	v_cmp_ne_u32_e32 vcc, 0, v96
	s_nop 1
	v_cndmask_b32_e32 v96, v187, v101, vcc
	v_bfe_i32 v101, v128, 1, 1
	v_bfi_b32 v97, v101, v97, v187
	v_and_b32_e32 v101, 4, v126
	v_cmp_ne_u32_e32 vcc, 0, v101
	s_nop 1
	v_cndmask_b32_e32 v101, v187, v102, vcc
	v_bfe_i32 v102, v128, 2, 1
	v_bfi_b32 v98, v102, v98, v187
	v_and_b32_e32 v102, 8, v126
	v_lshrrev_b32_e32 v126, v132, v129
	v_cmp_ne_u32_e32 vcc, 0, v102
	s_nop 1
	v_cndmask_b32_e32 v102, v187, v103, vcc
	v_and_b32_e32 v103, 8, v128
	v_cmp_ne_u32_e32 vcc, 0, v103
	s_nop 1
	v_cndmask_b32_e32 v103, v187, v99, vcc
	v_lshrrev_b32_e32 v99, v132, v127
	v_bfe_i32 v128, v99, 0, 1
	v_bfi_b32 v84, v128, v84, v187
	v_and_b32_e32 v128, 1, v126
	v_cmp_eq_u32_e32 vcc, 1, v128
	s_nop 1
	v_cndmask_b32_e32 v128, v187, v80, vcc
	v_and_b32_e32 v80, 2, v99
	v_cmp_ne_u32_e32 vcc, 0, v80
	s_nop 1
	v_cndmask_b32_e32 v80, v187, v85, vcc
	v_bfe_i32 v85, v126, 1, 1
	v_bfi_b32 v81, v85, v81, v187
	v_and_b32_e32 v85, 4, v99
	v_cmp_ne_u32_e32 vcc, 0, v85
	s_nop 1
	v_cndmask_b32_e32 v85, v187, v86, vcc
	v_bfe_i32 v86, v126, 2, 1
	v_bfi_b32 v155, v86, v82, v187
	v_bfe_i32 v86, v126, 3, 1
	v_and_b32_e32 v82, 8, v99
	v_cmp_ne_u32_e32 vcc, 0, v82
	s_nop 1
	v_cndmask_b32_e32 v82, v187, v87, vcc
	v_bfi_b32 v83, v86, v83, v187
	v_lshrrev_b32_e32 v86, v138, v127
	v_lshrrev_b32_e32 v87, v138, v129
	v_bfe_i32 v99, v86, 0, 1
	v_bfi_b32 v88, v99, v88, v187
	v_bfe_i32 v99, v87, 0, 1
	v_bfi_b32 v126, v99, v92, v187
	v_bfe_i32 v92, v86, 1, 1
	v_bfi_b32 v89, v92, v89, v187
	v_bfe_i32 v92, v87, 1, 1
	v_bfi_b32 v127, v92, v93, v187
	v_bfe_i32 v92, v86, 2, 1
	v_bfe_i32 v86, v86, 3, 1
	v_bfi_b32 v93, v92, v90, v187
	v_bfe_i32 v90, v87, 2, 1
	v_bfi_b32 v129, v90, v94, v187
	v_bfi_b32 v91, v86, v91, v187
	v_bfe_i32 v86, v87, 3, 1
	v_bfi_b32 v156, v86, v95, v187
	v_max_f32_e32 v86, v144, v145
	v_max_f32_e32 v87, v101, v102
	v_max_f32_e32 v90, v84, v80
	v_max_f32_e32 v92, v85, v82
	v_max_f32_e32 v94, v93, v91
	v_max3_f32 v94, v88, v89, v94
	v_max3_f32 v86, v159, v154, v86
	v_max3_f32 v87, v100, v96, v87
	v_max3_f32 v90, v90, v92, v94
	v_max3_f32 v86, v86, v87, v90
	v_mov_b32_e32 v87, v86
	s_waitcnt lgkmcnt(0)
	s_nop 1
	v_permlane16_swap_b32_e32 v86, v87
	v_max_f32_e32 v86, v86, v87
	v_mov_b32_e32 v87, v86
	s_waitcnt lgkmcnt(0)
; DI float softmax_step(f32x4 (&st)[4], float& m, float& lsum) {
;   float mx = fmaxf(fmaxf(fmaxf(st[0][0], st[0][1]), fmaxf(st[0][2], st[0][3])), fmaxf(fmaxf(st[1][0], st[1][1]), fmaxf(st[1][2], st[1][3])));
;   mx = fmaxf(mx, fmaxf(fmaxf(fmaxf(st[2][0], st[2][1]), fmaxf(st[2][2], st[2][3])), fmaxf(fmaxf(st[3][0], st[3][1]), fmaxf(st[3][2], st[3][3]))));
;   mx = fmaxf(mx, __shfl_xor(mx, 16)); mx = fmaxf(mx, __shfl_xor(mx, 32));
;   const float mn = fmaxf(m, mx);
;   const float mu = mn == -INFINITY ? 0.f : mn;
;   const float alpha = __builtin_amdgcn_exp2f(m - mu);
;   float ps = 0.f;
; #pragma unroll
;   for (int kt = 0; kt < 4; ++kt)
; #pragma unroll
;     for (int j = 0; j < 4; ++j) { const float p = __builtin_amdgcn_exp2f(st[kt][j] - mu); st[kt][j] = p; ps += p; }
;   lsum = lsum * alpha + ps; m = mn;
;   return alpha;
; }
	s_nop 1
	v_permlane32_swap_b32_e32 v86, v87
	v_max3_f32 v99, v131, v86, v87
	v_cmp_neq_f32_e32 vcc, s16, v99
	s_nop 1
	v_cndmask_b32_e32 v87, 0, v99, vcc
	v_sub_f32_e32 v86, v159, v87
	v_exp_f32_e32 v162, v86
	v_sub_f32_e32 v86, v154, v87
	v_exp_f32_e32 v164, v86
	v_sub_f32_e32 v86, v144, v87
	v_exp_f32_e32 v166, v86
	v_sub_f32_e32 v86, v145, v87
	v_sub_f32_e32 v80, v80, v87
	v_exp_f32_e32 v168, v86
	v_sub_f32_e32 v86, v100, v87
	v_exp_f32_e32 v94, v80
	v_sub_f32_e32 v80, v85, v87
	v_exp_f32_e32 v170, v86
	v_sub_f32_e32 v86, v96, v87
	v_exp_f32_e32 v92, v80
	v_sub_f32_e32 v80, v82, v87
	v_exp_f32_e32 v190, v86
	v_sub_f32_e32 v86, v101, v87
	v_exp_f32_e32 v90, v80
	v_sub_f32_e32 v80, v88, v87
	v_exp_f32_e32 v192, v86
	v_sub_f32_e32 v86, v102, v87
	v_exp_f32_e32 v88, v80
	v_sub_f32_e32 v80, v89, v87
	v_exp_f32_e32 v194, v86
	v_sub_f32_e32 v84, v84, v87
	v_exp_f32_e32 v86, v80
	v_sub_f32_e32 v80, v93, v87
	v_exp_f32_e32 v96, v84
	v_exp_f32_e32 v82, v80
	v_sub_f32_e32 v80, v91, v87
	v_sub_f32_e32 v84, v131, v87
	v_max_f32_e32 v85, v142, v143
	v_max_f32_e32 v87, v98, v103
	v_max_f32_e32 v89, v128, v81
	v_max_f32_e32 v91, v155, v83
	v_max_f32_e32 v93, v129, v156
	v_max3_f32 v93, v126, v127, v93
	v_max3_f32 v85, v130, v141, v85
	v_max3_f32 v87, v147, v97, v87
	v_max3_f32 v89, v89, v91, v93
	v_max3_f32 v85, v85, v87, v89
	v_mov_b32_e32 v87, v85
	v_exp_f32_e32 v84, v84
	v_exp_f32_e32 v80, v80
	v_mov_b32_e32 v131, v99
	s_waitcnt lgkmcnt(0)
	s_nop 1
	v_permlane16_swap_b32_e32 v85, v87
	v_max_f32_e32 v85, v85, v87
	v_mov_b32_e32 v87, v85
	s_waitcnt lgkmcnt(0)
	s_nop 1
	v_permlane32_swap_b32_e32 v85, v87
	v_max3_f32 v102, v146, v85, v87
	v_cmp_neq_f32_e32 vcc, s16, v102
	s_nop 1
	v_cndmask_b32_e32 v85, 0, v102, vcc
	v_sub_f32_e32 v87, v130, v85
	v_exp_f32_e32 v163, v87
	v_sub_f32_e32 v87, v141, v85
	v_exp_f32_e32 v165, v87
	v_sub_f32_e32 v87, v142, v85
	v_exp_f32_e32 v167, v87
	v_sub_f32_e32 v87, v143, v85
	v_exp_f32_e32 v169, v87
	v_sub_f32_e32 v87, v147, v85
	v_sub_f32_e32 v81, v81, v85
	v_exp_f32_e32 v171, v87
	v_sub_f32_e32 v87, v97, v85
	v_exp_f32_e32 v95, v81
	v_sub_f32_e32 v81, v155, v85
	v_exp_f32_e32 v191, v87
	v_sub_f32_e32 v87, v98, v85
	v_exp_f32_e32 v93, v81
	v_sub_f32_e32 v81, v83, v85
	v_exp_f32_e32 v193, v87
	v_sub_f32_e32 v87, v103, v85
	v_exp_f32_e32 v91, v81
	v_sub_f32_e32 v81, v126, v85
	v_exp_f32_e32 v195, v87
	v_sub_f32_e32 v87, v128, v85
	v_exp_f32_e32 v89, v81
	v_sub_f32_e32 v81, v127, v85
	v_exp_f32_e32 v97, v87
	v_exp_f32_e32 v87, v81
	v_sub_f32_e32 v81, v129, v85
	v_exp_f32_e32 v83, v81
	v_sub_f32_e32 v81, v156, v85
	v_sub_f32_e32 v85, v146, v85
	v_exp_f32_e32 v98, v85
	v_pk_mul_f32 v[156:157], v[70:71], v[84:85] op_sel_hi:[1,0]
	v_pk_mul_f32 v[154:155], v[68:69], v[84:85] op_sel_hi:[1,0]
	v_pk_mul_f32 v[128:129], v[62:63], v[84:85] op_sel_hi:[1,0]
	v_pk_mul_f32 v[142:143], v[56:57], v[98:99] op_sel_hi:[1,0]
	v_pk_mul_f32 v[70:71], v[50:51], v[98:99] op_sel_hi:[1,0]
	v_pk_mul_f32 v[68:69], v[48:49], v[98:99] op_sel_hi:[1,0]
	v_pk_mul_f32 v[50:51], v[74:75], v[84:85] op_sel_hi:[1,0]
	v_pk_mul_f32 v[48:49], v[72:73], v[84:85] op_sel_hi:[1,0]
	v_pk_add_f32 v[56:57], v[162:163], 0 op_sel_hi:[1,0]
	ds_read_b128 v[200:203], v139 offset:9216
	ds_read_b128 v[204:207], v139 offset:11264
	ds_read_b128 v[208:211], v139 offset:13312
	ds_read_b128 v[212:215], v139 offset:15360
	ds_read_b128 v[220:223], v140 offset:9216
	ds_read_b128 v[224:227], v140 offset:11264
	ds_read_b128 v[228:231], v140 offset:15360
	ds_read_b128 v[232:235], v140 offset:13312
	v_pk_add_f32 v[56:57], v[164:165], v[56:57]
	v_pk_mul_f32 v[126:127], v[60:61], v[84:85] op_sel_hi:[1,0]
	v_pk_add_f32 v[56:57], v[166:167], v[56:57]
	v_pk_mul_f32 v[144:145], v[58:59], v[98:99] op_sel_hi:[1,0]
	v_pk_add_f32 v[56:57], v[168:169], v[56:57]
	v_cvt_pk_f16_f32 v58, v170, v190
	v_pk_add_f32 v[56:57], v[170:171], v[56:57]
	v_cvt_pk_f16_f32 v59, v192, v194
	v_pk_add_f32 v[56:57], v[190:191], v[56:57]
	v_pk_mul_f32 v[160:161], v[66:67], v[98:99] op_sel_hi:[1,0]
	v_pk_add_f32 v[56:57], v[192:193], v[56:57]
	v_pk_mul_f32 v[158:159], v[64:65], v[98:99] op_sel_hi:[1,0]
	v_pk_add_f32 v[56:57], v[194:195], v[56:57]
	v_pk_mul_f32 v[66:67], v[54:55], v[84:85] op_sel_hi:[1,0]
	v_pk_add_f32 v[100:101], v[96:97], v[56:57]
	v_cvt_pk_f16_f32 v56, v162, v164
	v_cvt_pk_f16_f32 v57, v166, v168
	v_pk_mul_f32 v[64:65], v[52:53], v[84:85] op_sel_hi:[1,0]
	v_pk_mul_f32 v[54:55], v[78:79], v[98:99] op_sel_hi:[1,0]
	v_pk_mul_f32 v[52:53], v[76:77], v[98:99] op_sel_hi:[1,0]
	s_waitcnt lgkmcnt(7)
	v_mfma_f32_16x16x32_f16 v[76:79], v[200:203], v[56:59], v[126:129]
	v_cvt_pk_f16_f32 v60, v163, v165
	v_cvt_pk_f16_f32 v61, v167, v169
	v_cvt_pk_f16_f32 v62, v171, v191
	v_cvt_pk_f16_f32 v63, v193, v195
	v_exp_f32_e32 v81, v81
	v_cvt_pk_f16_f32 v190, v96, v94
	v_mfma_f32_16x16x32_f16 v[72:75], v[200:203], v[60:63], v[142:145]
	v_cvt_pk_f16_f32 v191, v92, v90
	v_cvt_pk_f16_f32 v192, v88, v86
	v_cvt_pk_f16_f32 v193, v82, v80
	s_waitcnt lgkmcnt(6)
	v_mfma_f32_16x16x32_f16 v[142:145], v[204:207], v[56:59], v[154:157]
	v_cvt_pk_f16_f32 v194, v97, v95
	v_cvt_pk_f16_f32 v195, v93, v91
	s_nop 0
	v_mfma_f32_16x16x32_f16 v[126:129], v[204:207], v[60:63], v[158:161]
	v_cvt_pk_f16_f32 v196, v89, v87
	v_cvt_pk_f16_f32 v197, v83, v81
	v_pk_add_f32 v[94:95], v[94:95], v[100:101]
	s_waitcnt lgkmcnt(5)
	v_mfma_f32_16x16x32_f16 v[158:161], v[208:211], v[56:59], v[64:67]
	s_nop 2
	v_pk_add_f32 v[92:93], v[92:93], v[94:95]
	v_mov_b32_e32 v85, v98
	s_waitcnt lgkmcnt(4)
	v_mfma_f32_16x16x32_f16 v[162:165], v[212:215], v[56:59], v[48:51]
	s_nop 2
	v_pk_add_f32 v[90:91], v[90:91], v[92:93]
	v_mov_b32_e32 v146, v102
	v_mfma_f32_16x16x32_f16 v[154:157], v[208:211], v[60:63], v[68:71]
	v_add_f32_e64 v88, v88, v90
	v_add_f32_e64 v89, v89, v91
	v_pk_add_f32 v[86:87], v[86:87], v[88:89]
	v_mfma_f32_16x16x32_f16 v[166:169], v[212:215], v[60:63], v[52:55]
	v_add_f32_e64 v82, v82, v86
	v_add_f32_e64 v83, v83, v87
	v_pk_add_f32 v[80:81], v[80:81], v[82:83]
	s_waitcnt lgkmcnt(3)
	v_mfma_f32_16x16x32_f16 v[60:63], v[220:223], v[190:193], v[76:79]
	v_fma_f32 v118, v118, v84, v80
	v_fma_f32 v119, v119, v85, v81
	v_mfma_f32_16x16x32_f16 v[56:59], v[220:223], v[194:197], v[72:75]
	s_waitcnt lgkmcnt(2)
	v_mfma_f32_16x16x32_f16 v[68:71], v[224:227], v[190:193], v[142:145]
	v_mfma_f32_16x16x32_f16 v[64:67], v[224:227], v[194:197], v[126:129]
	s_waitcnt lgkmcnt(0)
	v_mfma_f32_16x16x32_f16 v[52:55], v[232:235], v[190:193], v[158:161]
	v_mfma_f32_16x16x32_f16 v[48:51], v[232:235], v[194:197], v[154:157]
	v_mfma_f32_16x16x32_f16 v[72:75], v[228:231], v[190:193], v[162:165]
	v_mfma_f32_16x16x32_f16 v[76:79], v[228:231], v[194:197], v[166:169]
